# dilated attention P.V section: V fragment reads four MFMAs ahead (two extra fragment buffers), counted lgkmcnt waits re-derived
# baseline (speedup 1.0000x reference)
; __device__ __forceinline__ float shx(float v, int m, int lane) { return __builtin_bit_cast(float, __builtin_amdgcn_ds_bpermute((lane ^ m) << 2, __builtin_bit_cast(int, v))); }
; __device__ __forceinline__ int crow(int r,int hi){return (r&3)+8*(r>>2)+4*hi;}
; __device__ __forceinline__ float shx(float v, int m, int lane) { return __builtin_bit_cast(float, __builtin_amdgcn_ds_bpermute((lane ^ m) << 2, __builtin_bit_cast(int, v))); }
; __device__ __forceinline__ int crow(int reg, int h) { return (reg & 3) + 8 * (reg >> 2) + 4 * h; }
; __device__ __forceinline__ void phase(LAS unsigned char* L, const u16* __restrict__ QKV, u16* OBg0, u16* OBg1, u16* OBg2, float* LSE, int first, int stride, const int tid) {
;     ...
;         float m = -INFINITY;
;         const int kneg = 128 - i0 - 32 * w;
; #pragma unroll
;         for (int i = 0; i < 16; ++i) { const int c = crow(i, h);
;             X[0][i] = (c >= r && c >= kneg) ? X[0][i] : -INFINITY; X[4][i] = (c <= r) ? X[4][i] : -INFINITY; }
;         if (kneg > 32) {
; #pragma unroll
;             for (int kb = 1; kb < 4; ++kb)
; #pragma unroll
;                 for (int i = 0; i < 16; ++i) X[kb][i] = (32 * kb + crow(i, h) >= kneg) ? X[kb][i] : -INFINITY;
;         }
; #pragma unroll
;         for (int kb = 0; kb < 5; ++kb)
; #pragma unroll
;             for (int i = 0; i < 16; i += 2) m = fmaxf(m, fmaxf(X[kb][i], X[kb][i + 1]));
;         m = fmaxf(m, shx(m, 32, lane));
;         float l = 0.f;
; #pragma unroll
;         for (int kb = 0; kb < 5; ++kb)
; #pragma unroll
;             for (int i = 0; i < 16; ++i) { X[kb][i] = __builtin_amdgcn_exp2f(X[kb][i] - m); l += X[kb][i]; }
;         l += shx(l, 32, lane);
.LBB0_482:
	v_cmp_gt_i32_e32 vcc, s13, v170
	s_or_b64 vcc, s[2:3], vcc
	s_nop 8
	v_cndmask_b32_e64 v146, v248, v67, s[2:3]
	v_cndmask_b32_e32 v150, v50, v248, vcc
	v_cmp_gt_i32_e32 vcc, s13, v172
	s_or_b64 vcc, s[76:77], vcc
	v_cndmask_b32_e64 v67, v71, v248, s[30:31]
	v_cndmask_b32_e32 v151, v51, v248, vcc
	v_cmp_gt_i32_e32 vcc, s13, v173
	s_or_b64 vcc, s[16:17], vcc
	v_cndmask_b32_e64 v147, v68, v248, s[18:19]
	v_cndmask_b32_e32 v152, v52, v248, vcc
	v_cmp_gt_i32_e32 vcc, s13, v174
	s_or_b64 vcc, s[20:21], vcc
	v_cndmask_b32_e64 v68, v72, v248, s[36:37]
	v_cndmask_b32_e32 v153, v53, v248, vcc
	v_cmp_gt_i32_e32 vcc, s13, v175
	s_or_b64 vcc, s[24:25], vcc
	v_cndmask_b32_e64 v148, v69, v248, s[22:23]
	v_cndmask_b32_e32 v154, v54, v248, vcc
	v_cmp_gt_i32_e32 vcc, s13, v176
	s_or_b64 vcc, s[28:29], vcc
	v_cndmask_b32_e64 v69, v73, v248, s[40:41]
	v_cndmask_b32_e32 v155, v55, v248, vcc
	v_cmp_gt_i32_e32 vcc, s13, v177
	s_or_b64 vcc, s[34:35], vcc
	v_readlane_b32 s50, v254, 12
	v_cndmask_b32_e32 v71, v56, v248, vcc
	v_cmp_gt_i32_e32 vcc, s13, v178
	s_or_b64 vcc, s[38:39], vcc
	v_readlane_b32 s51, v254, 13
	v_cndmask_b32_e32 v72, v57, v248, vcc
	v_cmp_gt_i32_e32 vcc, s13, v179
	s_or_b64 vcc, s[42:43], vcc
	v_cndmask_b32_e64 v149, v66, v248, s[50:51]
	v_cndmask_b32_e32 v73, v58, v248, vcc
	v_cmp_gt_i32_e32 vcc, s13, v180
	s_or_b64 vcc, s[46:47], vcc
	v_readlane_b32 s50, v254, 18
	v_cndmask_b32_e32 v59, v59, v248, vcc
	v_cmp_gt_i32_e32 vcc, s13, v181
	s_or_b64 vcc, s[4:5], vcc
	v_readlane_b32 s51, v254, 19
	v_cndmask_b32_e32 v60, v60, v248, vcc
	v_cmp_gt_i32_e32 vcc, s13, v182
	s_or_b64 vcc, s[54:55], vcc
	v_cndmask_b32_e32 v61, v61, v248, vcc
	v_cmp_gt_i32_e32 vcc, s13, v183
	s_or_b64 vcc, s[58:59], vcc
	v_cndmask_b32_e32 v62, v62, v248, vcc
	v_cmp_gt_i32_e32 vcc, s13, v184
	s_or_b64 vcc, s[62:63], vcc
	v_cndmask_b32_e64 v66, v74, v248, s[44:45]
	v_cndmask_b32_e32 v63, v63, v248, vcc
	v_cmp_gt_i32_e32 vcc, s13, v185
	s_or_b64 vcc, s[50:51], vcc
	v_cndmask_b32_e32 v64, v64, v248, vcc
	v_cmp_gt_i32_e32 vcc, s13, v186
	s_mov_b32 s13, 0xff800000
	v_cndmask_b32_e64 v56, v75, v248, s[48:49]
	v_readlane_b32 s50, v254, 16
	s_nop 1
	v_readlane_b32 s51, v254, 17
	s_nop 1
	v_cndmask_b32_e64 v53, v80, v248, s[50:51]
	v_readlane_b32 s50, v254, 20
	s_nop 1
	v_readlane_b32 s51, v254, 21
	s_nop 1
	s_or_b64 vcc, s[50:51], vcc
	v_cndmask_b32_e32 v65, v65, v248, vcc
	v_cndmask_b32_e64 v70, v70, v248, s[26:27]
	v_cndmask_b32_e64 v57, v76, v248, s[52:53]
	v_cndmask_b32_e64 v58, v77, v248, s[56:57]
	v_readlane_b32 s50, v254, 22
	v_cndmask_b32_e64 v55, v78, v248, s[60:61]
	v_cndmask_b32_e64 v51, v79, v248, s[64:65]
	v_readlane_b32 s51, v254, 23
	s_nop 1
	v_cndmask_b32_e64 v54, v81, v248, s[50:51]
	v_max3_f32 v52, v151, v150, v153
	v_max3_f32 v74, v152, v155, v154
	v_max3_f32 v52, v52, v72, v71
	v_max3_f32 v74, v74, v59, v73
	v_max3_f32 v52, v52, v61, v60
	v_max3_f32 v74, v74, v63, v62
	v_max3_f32 v52, v52, v65, v64
	v_max3_f32 v74, v74, v35, v34
	v_max3_f32 v52, v52, v37, v36
	v_max3_f32 v74, v74, v39, v38
	v_max3_f32 v52, v52, v41, v40
	v_max3_f32 v74, v74, v43, v42
	v_max3_f32 v52, v52, v45, v44
	v_max3_f32 v74, v74, v47, v46
	v_max3_f32 v52, v52, v49, v48
	v_max3_f32 v74, v74, v19, v18
	v_max3_f32 v52, v52, v21, v20
	v_max3_f32 v74, v74, v23, v22
	v_max3_f32 v52, v52, v25, v24
	v_max3_f32 v74, v74, v27, v26
	v_max3_f32 v52, v52, v29, v28
	v_max3_f32 v74, v74, v31, v30
	v_max3_f32 v52, v52, v33, v32
	v_max3_f32 v74, v74, v3, v2
	v_max3_f32 v52, v52, v5, v4
	v_max3_f32 v74, v74, v7, v6
	v_max3_f32 v52, v52, v9, v8
	v_max3_f32 v74, v74, v11, v10
	v_max3_f32 v52, v52, v13, v12
	v_max3_f32 v74, v74, v15, v14
	v_max3_f32 v52, v52, v17, v16
	v_max3_f32 v74, v74, v146, v149
	v_max3_f32 v52, v52, v148, v147
	v_max3_f32 v74, v74, v67, v70
	v_max3_f32 v52, v52, v69, v68
	v_max3_f32 v74, v74, v56, v66
	v_max3_f32 v52, v52, v58, v57
	v_max3_f32 v74, v74, v51, v55
	v_max3_f32 v52, v52, v54, v53
	v_max_f32_e32 v52, v52, v74
	ds_bpermute_b32 v74, v171, v52
	s_ashr_i32 vcc_lo, s68, 4
	s_sub_i32 s14, 5, s9
	v_or_b32_e32 v50, s12, v162
	s_ashr_i32 vcc_hi, vcc_lo, 31
	s_waitcnt lgkmcnt(0)
	v_max_f32_e32 v74, v74, v74
	v_max_f32_e32 v52, v52, v74
	v_sub_f32_e32 v74, v150, v52
	v_exp_f32_e32 v74, v74
	v_sub_f32_e32 v75, v151, v52
	v_exp_f32_e32 v75, v75
	v_sub_f32_e32 v76, v152, v52
	v_exp_f32_e32 v76, v76
	v_sub_f32_e32 v78, v153, v52
	v_exp_f32_e32 v78, v78
	v_sub_f32_e32 v79, v154, v52
	v_add_f32_e32 v77, 0, v74
	v_exp_f32_e32 v79, v79
	v_sub_f32_e32 v80, v155, v52
	v_add_f32_e32 v77, v75, v77
	v_exp_f32_e32 v80, v80
	v_sub_f32_e32 v71, v71, v52
	v_add_f32_e32 v77, v76, v77
	v_exp_f32_e32 v71, v71
	v_sub_f32_e32 v72, v72, v52
	v_add_f32_e32 v77, v78, v77
	v_exp_f32_e32 v72, v72
	v_sub_f32_e32 v73, v73, v52
	v_add_f32_e32 v77, v79, v77
	v_exp_f32_e32 v73, v73
	v_sub_f32_e32 v59, v59, v52
	v_add_f32_e32 v77, v80, v77
	v_exp_f32_e32 v59, v59
	v_sub_f32_e32 v60, v60, v52
	v_add_f32_e32 v77, v71, v77
	v_exp_f32_e32 v60, v60
	v_sub_f32_e32 v61, v61, v52
	v_add_f32_e32 v77, v72, v77
	v_exp_f32_e32 v61, v61
	v_sub_f32_e32 v62, v62, v52
	v_add_f32_e32 v77, v73, v77
	v_exp_f32_e32 v62, v62
	v_sub_f32_e32 v63, v63, v52
	v_add_f32_e32 v77, v59, v77
	v_exp_f32_e32 v63, v63
	v_sub_f32_e32 v64, v64, v52
	v_add_f32_e32 v77, v60, v77
	v_exp_f32_e32 v64, v64
	v_sub_f32_e32 v65, v65, v52
	v_add_f32_e32 v77, v61, v77
	v_exp_f32_e32 v65, v65
	v_sub_f32_e32 v34, v34, v52
	v_add_f32_e32 v77, v62, v77
	v_exp_f32_e32 v81, v34
	v_sub_f32_e32 v34, v35, v52
	v_add_f32_e32 v77, v63, v77
	v_exp_f32_e32 v150, v34
	v_sub_f32_e32 v34, v36, v52
	v_add_f32_e32 v77, v64, v77
	v_exp_f32_e32 v151, v34
	v_sub_f32_e32 v35, v37, v52
; __device__ __forceinline__ float shx(float v, int m, int lane) { return __builtin_bit_cast(float, __builtin_amdgcn_ds_bpermute((lane ^ m) << 2, __builtin_bit_cast(int, v))); }
; __device__ __forceinline__ float shx(float v, int m, int lane) { return __builtin_bit_cast(float, __builtin_amdgcn_ds_bpermute((lane ^ m) << 2, __builtin_bit_cast(int, v))); }
; #define MFMA32(a, b, c) __builtin_amdgcn_mfma_f32_32x32x16_bf16((a), (b), (c), 0, 0, 0)
; __device__ __forceinline__ void phase(LAS unsigned char* L, const u16* __restrict__ QKV, u16* OBg0, u16* OBg1, u16* OBg2, float* LSE, int first, int stride, const int tid) {
;     ...
;         float l = 0.f;
; #pragma unroll
;         for (int kb = 0; kb < 5; ++kb)
; #pragma unroll
;             for (int i = 0; i < 16; ++i) { X[kb][i] = __builtin_amdgcn_exp2f(X[kb][i] - m); l += X[kb][i]; }
;         l += shx(l, 32, lane);
;         f32x16 y[2]; y[0] = f32x16{}; y[1] = f32x16{};
; #pragma unroll
;         for (int kb = 0; kb < 5; ++kb) {
;             bf16x8 vf[2][2];
; #pragma unroll
;             for (int s2 = 0; s2 < 2; ++s2)
; #pragma unroll
;                 for (int dt = 0; dt < 2; ++dt) vf[s2][dt] = trfrag(L + O_V, VP, 32 * w + 32 * kb + 16 * s2 + 4 * h, 8, 32 * dt, lane);
;             const bf16x8 pb0 = pack8(X[kb], 0), pb1 = pack8(X[kb], 8);
;             y[0] = MFMA32(vf[0][0], pb0, y[0]); y[1] = MFMA32(vf[0][1], pb0, y[1]); y[0] = MFMA32(vf[1][0], pb1, y[0]); y[1] = MFMA32(vf[1][1], pb1, y[1]);
	v_add_f32_e32 v34, v65, v77
	v_exp_f32_e32 v77, v35
	v_sub_f32_e32 v35, v38, v52
	v_add_f32_e32 v34, v81, v34
	v_exp_f32_e32 v152, v35
	v_sub_f32_e32 v35, v39, v52
	v_add_f32_e32 v34, v150, v34
	v_exp_f32_e32 v153, v35
	v_sub_f32_e32 v35, v40, v52
	v_add_f32_e32 v34, v151, v34
	v_exp_f32_e32 v154, v35
	v_sub_f32_e32 v35, v41, v52
	v_add_f32_e32 v34, v77, v34
	v_exp_f32_e32 v155, v35
	v_sub_f32_e32 v35, v42, v52
	v_add_f32_e32 v34, v152, v34
	v_exp_f32_e32 v156, v35
	v_sub_f32_e32 v35, v43, v52
	v_add_f32_e32 v34, v153, v34
	v_exp_f32_e32 v157, v35
	v_sub_f32_e32 v35, v44, v52
	v_add_f32_e32 v34, v154, v34
	v_exp_f32_e32 v161, v35
	v_sub_f32_e32 v35, v45, v52
	v_add_f32_e32 v34, v155, v34
	v_exp_f32_e32 v204, v35
	v_sub_f32_e32 v35, v46, v52
	v_add_f32_e32 v34, v156, v34
	v_exp_f32_e32 v46, v35
	v_sub_f32_e32 v35, v47, v52
	v_add_f32_e32 v34, v157, v34
	v_exp_f32_e32 v47, v35
	v_sub_f32_e32 v35, v48, v52
	v_add_f32_e32 v34, v161, v34
	v_exp_f32_e32 v48, v35
	v_sub_f32_e32 v35, v49, v52
	v_add_f32_e32 v34, v204, v34
	v_exp_f32_e32 v49, v35
	v_sub_f32_e32 v18, v18, v52
	v_add_f32_e32 v34, v46, v34
	v_exp_f32_e32 v205, v18
	v_sub_f32_e32 v18, v19, v52
	v_add_f32_e32 v34, v47, v34
	v_exp_f32_e32 v206, v18
	v_sub_f32_e32 v18, v20, v52
	v_add_f32_e32 v34, v48, v34
	v_exp_f32_e32 v207, v18
	v_sub_f32_e32 v19, v21, v52
	v_add_f32_e32 v18, v49, v34
	v_exp_f32_e32 v221, v19
	v_sub_f32_e32 v19, v22, v52
	v_add_f32_e32 v18, v205, v18
	v_exp_f32_e32 v222, v19
	v_sub_f32_e32 v19, v23, v52
	v_add_f32_e32 v18, v206, v18
	v_exp_f32_e32 v223, v19
	v_sub_f32_e32 v19, v24, v52
	v_add_f32_e32 v18, v207, v18
	v_exp_f32_e32 v224, v19
	v_sub_f32_e32 v19, v25, v52
	v_add_f32_e32 v18, v221, v18
	v_exp_f32_e32 v225, v19
	v_sub_f32_e32 v19, v26, v52
	v_add_f32_e32 v18, v222, v18
	v_exp_f32_e32 v226, v19
	v_sub_f32_e32 v19, v27, v52
	v_add_f32_e32 v18, v223, v18
	v_exp_f32_e32 v227, v19
	v_sub_f32_e32 v19, v28, v52
	v_add_f32_e32 v18, v224, v18
	v_exp_f32_e32 v228, v19
	v_sub_f32_e32 v19, v29, v52
	v_add_f32_e32 v18, v225, v18
	v_exp_f32_e32 v229, v19
	v_sub_f32_e32 v19, v30, v52
	v_add_f32_e32 v18, v226, v18
	v_exp_f32_e32 v230, v19
	v_sub_f32_e32 v19, v31, v52
	v_add_f32_e32 v18, v227, v18
	v_exp_f32_e32 v231, v19
	v_sub_f32_e32 v19, v32, v52
	v_add_f32_e32 v18, v228, v18
	v_exp_f32_e32 v232, v19
	v_sub_f32_e32 v19, v33, v52
	v_add_f32_e32 v18, v229, v18
	v_exp_f32_e32 v233, v19
	v_sub_f32_e32 v2, v2, v52
	v_add_f32_e32 v18, v230, v18
	v_exp_f32_e32 v234, v2
	v_sub_f32_e32 v2, v3, v52
	v_add_f32_e32 v18, v231, v18
	v_exp_f32_e32 v235, v2
	v_sub_f32_e32 v2, v4, v52
	v_add_f32_e32 v18, v232, v18
	v_exp_f32_e32 v236, v2
	v_sub_f32_e32 v3, v5, v52
	v_add_f32_e32 v2, v233, v18
	v_exp_f32_e32 v237, v3
	v_sub_f32_e32 v3, v6, v52
	v_add_f32_e32 v2, v234, v2
	v_exp_f32_e32 v238, v3
	v_sub_f32_e32 v3, v7, v52
	v_add_f32_e32 v2, v235, v2
	v_exp_f32_e32 v239, v3
	v_sub_f32_e32 v3, v8, v52
	v_add_f32_e32 v2, v236, v2
	v_exp_f32_e32 v240, v3
	v_sub_f32_e32 v3, v9, v52
	v_add_f32_e32 v2, v237, v2
	v_exp_f32_e32 v241, v3
	v_sub_f32_e32 v3, v10, v52
	v_add_f32_e32 v2, v238, v2
	v_exp_f32_e32 v242, v3
	v_sub_f32_e32 v3, v11, v52
	v_add_f32_e32 v2, v239, v2
	v_exp_f32_e32 v243, v3
	v_sub_f32_e32 v3, v12, v52
	v_add_f32_e32 v2, v240, v2
	v_exp_f32_e32 v244, v3
	v_add_f32_e32 v2, v241, v2
	v_add_f32_e32 v2, v242, v2
	v_add_f32_e32 v2, v243, v2
	v_add_f32_e32 v6, v244, v2
	v_sub_f32_e32 v2, v13, v52
	v_exp_f32_e32 v245, v2
	v_sub_f32_e32 v2, v14, v52
	v_exp_f32_e32 v251, v2
	ds_read_b64_tr_b16 v[2:3], v200 offset:55296
	ds_read_b64_tr_b16 v[4:5], v200 offset:56832
	v_add_f32_e32 v6, v245, v6
	v_cvt_pk_bf16_f32 v10, v74, v75
	v_cvt_pk_bf16_f32 v11, v76, v78
	v_cvt_pk_bf16_f32 v12, v79, v80
	v_cvt_pk_bf16_f32 v13, v71, v72
	v_add_f32_e32 v252, v251, v6
	ds_read_b64_tr_b16 v[8:9], v200 offset:56896
	ds_read_b64_tr_b16 v[6:7], v200 offset:55360
	s_waitcnt lgkmcnt(2)
	v_mfma_f32_32x32x16_bf16 v[18:33], v[2:5], v[10:13], 0
	v_sub_f32_e32 v2, v15, v52
	ds_read_b64_tr_b16 v[34:35], v200 offset:58368
	ds_read_b64_tr_b16 v[36:37], v200 offset:59904
	v_exp_f32_e32 v71, v2
	v_sub_f32_e32 v2, v16, v52
	v_exp_f32_e32 v72, v2
	v_sub_f32_e32 v38, v17, v52
	v_exp_f32_e32 v74, v38
	s_waitcnt lgkmcnt(2)
	v_mfma_f32_32x32x16_bf16 v[2:17], v[6:9], v[10:13], 0
	v_cvt_pk_bf16_f32 v42, v73, v59
	v_cvt_pk_bf16_f32 v43, v60, v61
	v_cvt_pk_bf16_f32 v44, v62, v63
	v_cvt_pk_bf16_f32 v45, v64, v65
	ds_read_b64_tr_b16 v[40:41], v200 offset:59968
	ds_read_b64_tr_b16 v[38:39], v200 offset:58432
	v_sub_f32_e32 v63, v148, v52
	v_exp_f32_e32 v63, v63
	s_waitcnt lgkmcnt(2)
	v_mfma_f32_32x32x16_bf16 v[18:33], v[34:37], v[42:45], v[18:33]
	v_add_f32_e32 v34, v71, v252
	v_add_f32_e32 v34, v72, v34
	v_add_f32_e32 v59, v74, v34
	v_sub_f32_e32 v34, v149, v52
	v_exp_f32_e32 v60, v34
	ds_read_b64_tr_b16 v[34:35], v200 offset:61440
	ds_read_b64_tr_b16 v[36:37], v200 offset:62976
	v_sub_f32_e32 v58, v58, v52
	s_waitcnt lgkmcnt(2)
	v_mfma_f32_32x32x16_bf16 v[2:17], v[38:41], v[42:45], v[2:17]
	v_cvt_pk_bf16_f32 v42, v81, v150
	v_cvt_pk_bf16_f32 v43, v151, v77
	v_cvt_pk_bf16_f32 v44, v152, v153
	v_cvt_pk_bf16_f32 v45, v154, v155
	ds_read_b64_tr_b16 v[40:41], v200 offset:63040
	ds_read_b64_tr_b16 v[38:39], v200 offset:61504
	ds_read_b64_tr_b16 v[148:149], v200 offset:64512
	ds_read_b64_tr_b16 v[150:151], v201 offset:1536
	v_add_f32_e32 v59, v60, v59
	v_exp_f32_e32 v58, v58
	s_waitcnt lgkmcnt(4)
	v_mfma_f32_32x32x16_bf16 v[18:33], v[34:37], v[42:45], v[18:33]
	v_sub_f32_e32 v34, v146, v52
	v_exp_f32_e32 v61, v34
	v_sub_f32_e32 v34, v147, v52
	v_exp_f32_e32 v62, v34
	ds_read_b64_tr_b16 v[154:155], v202 offset:1536
	ds_read_b64_tr_b16 v[152:153], v200 offset:64576
	ds_read_b64_tr_b16 v[34:35], v220 offset:12288
	ds_read_b64_tr_b16 v[36:37], v220 offset:13824
	s_lshr_b32 s11, s11, s14
	v_lshlrev_b32_e32 v50, s9, v50
	s_waitcnt lgkmcnt(6)
; #define MFMA32(a, b, c) __builtin_amdgcn_mfma_f32_32x32x16_bf16((a), (b), (c), 0, 0, 0)
; __device__ __forceinline__ void phase(LAS unsigned char* L, const u16* __restrict__ QKV, u16* OBg0, u16* OBg1, u16* OBg2, float* LSE, int first, int stride, const int tid) {
;     ...
;         for (int kb = 0; kb < 5; ++kb) {
;             bf16x8 vf[2][2];
; #pragma unroll
;             for (int s2 = 0; s2 < 2; ++s2)
; #pragma unroll
;                 for (int dt = 0; dt < 2; ++dt) vf[s2][dt] = trfrag(L + O_V, VP, 32 * w + 32 * kb + 16 * s2 + 4 * h, 8, 32 * dt, lane);
;             const bf16x8 pb0 = pack8(X[kb], 0), pb1 = pack8(X[kb], 8);
;             y[0] = MFMA32(vf[0][0], pb0, y[0]); y[1] = MFMA32(vf[0][1], pb0, y[1]); y[0] = MFMA32(vf[1][0], pb1, y[0]); y[1] = MFMA32(vf[1][1], pb1, y[1]);
;         }
	v_mfma_f32_32x32x16_bf16 v[2:17], v[38:41], v[42:45], v[2:17]
	v_cvt_pk_bf16_f32 v42, v156, v157
	v_cvt_pk_bf16_f32 v43, v161, v204
	v_cvt_pk_bf16_f32 v44, v46, v47
	v_cvt_pk_bf16_f32 v45, v48, v49
	ds_read_b64_tr_b16 v[40:41], v220 offset:13888
	ds_read_b64_tr_b16 v[38:39], v220 offset:12352
	s_and_b32 s9, s68, 15
	s_lshl_b64 s[12:13], vcc, 13
	s_waitcnt lgkmcnt(6)
	v_mfma_f32_32x32x16_bf16 v[18:33], v[148:151], v[42:45], v[18:33]
	v_add_f32_e32 v80, v61, v59
	v_add_f32_e32 v80, v62, v80
	v_add_f32_e32 v46, v63, v80
	v_sub_f32_e32 v80, v70, v52
	v_exp_f32_e32 v47, v80
	ds_read_b64_tr_b16 v[148:149], v220 offset:15360
	ds_read_b64_tr_b16 v[150:151], v220 offset:16896
	v_sub_f32_e32 v59, v69, v52
	s_waitcnt lgkmcnt(6)
	v_mfma_f32_32x32x16_bf16 v[2:17], v[152:155], v[42:45], v[2:17]
	v_cvt_pk_bf16_f32 v42, v205, v206
	v_cvt_pk_bf16_f32 v43, v207, v221
	v_cvt_pk_bf16_f32 v44, v222, v223
	v_cvt_pk_bf16_f32 v45, v224, v225
	ds_read_b64_tr_b16 v[154:155], v220 offset:16960
	ds_read_b64_tr_b16 v[152:153], v220 offset:15424
	v_exp_f32_e32 v59, v59
	v_add_f32_e32 v46, v47, v46
	s_waitcnt lgkmcnt(6)
	v_mfma_f32_32x32x16_bf16 v[18:33], v[34:37], v[42:45], v[18:33]
	v_sub_f32_e32 v34, v67, v52
	v_exp_f32_e32 v48, v34
	v_sub_f32_e32 v34, v68, v52
	v_exp_f32_e32 v49, v34
	ds_read_b64_tr_b16 v[34:35], v220 offset:18432
	ds_read_b64_tr_b16 v[36:37], v220 offset:19968
	v_add_u32_e32 v50, s11, v50
	s_cmp_eq_u32 s0, 1
	s_waitcnt lgkmcnt(6)
	v_mfma_f32_32x32x16_bf16 v[2:17], v[38:41], v[42:45], v[2:17]
	v_cvt_pk_bf16_f32 v42, v226, v227
	v_cvt_pk_bf16_f32 v43, v228, v229
	v_cvt_pk_bf16_f32 v44, v230, v231
	v_cvt_pk_bf16_f32 v45, v232, v233
	ds_read_b64_tr_b16 v[40:41], v220 offset:20032
	ds_read_b64_tr_b16 v[38:39], v220 offset:18496
	v_readlane_b32 s11, v255, 1
	v_readlane_b32 s14, v255, 2
	s_waitcnt lgkmcnt(6)
	v_mfma_f32_32x32x16_bf16 v[18:33], v[148:151], v[42:45], v[18:33]
	v_add_f32_e32 v80, v48, v46
	v_add_f32_e32 v80, v49, v80
	v_add_f32_e32 v46, v59, v80
	v_sub_f32_e32 v80, v66, v52
	v_exp_f32_e32 v64, v80
	ds_read_b64_tr_b16 v[148:149], v220 offset:21504
	ds_read_b64_tr_b16 v[150:151], v220 offset:23040
	s_cselect_b32 s11, s11, s80
	s_waitcnt lgkmcnt(6)
	v_mfma_f32_32x32x16_bf16 v[2:17], v[152:155], v[42:45], v[2:17]
	v_cvt_pk_bf16_f32 v42, v234, v235
	v_cvt_pk_bf16_f32 v43, v236, v237
	v_cvt_pk_bf16_f32 v44, v238, v239
	v_cvt_pk_bf16_f32 v45, v240, v241
	ds_read_b64_tr_b16 v[154:155], v220 offset:23104
	ds_read_b64_tr_b16 v[152:153], v220 offset:21568
	v_add_f32_e32 v46, v64, v46
	s_cselect_b32 s14, s14, s81
	s_waitcnt lgkmcnt(6)
	v_mfma_f32_32x32x16_bf16 v[18:33], v[34:37], v[42:45], v[18:33]
	v_sub_f32_e32 v34, v56, v52
	v_exp_f32_e32 v56, v34
	v_sub_f32_e32 v34, v57, v52
	v_exp_f32_e32 v57, v34
	ds_read_b64_tr_b16 v[34:35], v220 offset:24576
	ds_read_b64_tr_b16 v[36:37], v220 offset:26112
	s_cmp_lt_u32 s1, 32
	v_readlane_b32 s1, v253, 58
	s_waitcnt lgkmcnt(6)
	v_mfma_f32_32x32x16_bf16 v[2:17], v[38:41], v[42:45], v[2:17]
	v_cvt_pk_bf16_f32 v42, v242, v243
	v_cvt_pk_bf16_f32 v43, v244, v245
	v_cvt_pk_bf16_f32 v44, v251, v71
	v_cvt_pk_bf16_f32 v45, v72, v74
	ds_read_b64_tr_b16 v[40:41], v220 offset:26176
	ds_read_b64_tr_b16 v[38:39], v220 offset:24640
	s_cselect_b32 s15, s1, s14
	v_readlane_b32 s1, v253, 57
	s_waitcnt lgkmcnt(6)
	v_mfma_f32_32x32x16_bf16 v[18:33], v[148:151], v[42:45], v[18:33]
	v_add_f32_e32 v80, v56, v46
	v_add_f32_e32 v80, v57, v80
	v_add_f32_e32 v46, v58, v80
	v_sub_f32_e32 v80, v55, v52
	v_exp_f32_e32 v55, v80
	ds_read_b64_tr_b16 v[148:149], v220 offset:27648
	ds_read_b64_tr_b16 v[150:151], v220 offset:29184
	s_cselect_b32 s14, s1, s11
	s_waitcnt lgkmcnt(6)
; __device__ __forceinline__ unsigned pk2(float lo, float hi) { f32x2_t v = {lo, hi}; bf16x2_t b = __builtin_convertvector(v, bf16x2_t); return __builtin_bit_cast(unsigned, b); }
; #define MFMA32(a, b, c) __builtin_amdgcn_mfma_f32_32x32x16_bf16((a), (b), (c), 0, 0, 0)
; __device__ __forceinline__ void phase(LAS unsigned char* L, const u16* __restrict__ QKV, u16* OBg0, u16* OBg1, u16* OBg2, float* LSE, int first, int stride, const int tid) {
;     ...
;         for (int kb = 0; kb < 5; ++kb) {
;             bf16x8 vf[2][2];
; #pragma unroll
;             for (int s2 = 0; s2 < 2; ++s2)
; #pragma unroll
;                 for (int dt = 0; dt < 2; ++dt) vf[s2][dt] = trfrag(L + O_V, VP, 32 * w + 32 * kb + 16 * s2 + 4 * h, 8, 32 * dt, lane);
;             const bf16x8 pb0 = pack8(X[kb], 0), pb1 = pack8(X[kb], 8);
;             y[0] = MFMA32(vf[0][0], pb0, y[0]); y[1] = MFMA32(vf[0][1], pb0, y[1]); y[0] = MFMA32(vf[1][0], pb1, y[0]); y[1] = MFMA32(vf[1][1], pb1, y[1]);
;         }
;         const float inv = __builtin_amdgcn_rcpf(l);
;         u16* ob = (g == 0 ? OBg0 : g == 1 ? OBg1 : OBg2) + (d.rowb + qpos) * 1024 + d.hd * 64;
; #pragma unroll
;         for (int dt = 0; dt < 2; ++dt)
; #pragma unroll
;             for (int gp = 0; gp < 2; ++gp) {
;                 const int ge = 2 * gp, go = 2 * gp + 1;
;                 unsigned e0 = pk2(y[dt][4 * ge] * inv, y[dt][4 * ge + 1] * inv), e1 = pk2(y[dt][4 * ge + 2] * inv, y[dt][4 * ge + 3] * inv);
;                 unsigned o0 = pk2(y[dt][4 * go] * inv, y[dt][4 * go + 1] * inv), o1 = pk2(y[dt][4 * go + 2] * inv, y[dt][4 * go + 3] * inv);
;                 const auto s0 = __builtin_amdgcn_permlane32_swap(e0, o0, false, false); const auto s1 = __builtin_amdgcn_permlane32_swap(e1, o1, false, false);
;                 const v4u wv = {s0[0], s1[0], s0[1], s1[1]};
;                 *(v4u*)(ob + 32 * dt + 8 * (2 * gp + h)) = wv; }
;         if (h == 0) LSE[((size_t)g * MTOK + d.rowb + qpos) * 16 + d.hd] = (m + __log2f(l)) * 0.6931471805599453f;
	v_mfma_f32_32x32x16_bf16 v[2:17], v[152:155], v[42:45], v[2:17]
	v_cvt_pk_bf16_f32 v42, v60, v61
	v_cvt_pk_bf16_f32 v43, v62, v63
	v_cvt_pk_bf16_f32 v44, v47, v48
	v_cvt_pk_bf16_f32 v45, v49, v59
	ds_read_b64_tr_b16 v[154:155], v220 offset:29248
	ds_read_b64_tr_b16 v[152:153], v220 offset:27712
	v_sub_f32_e32 v49, v54, v52
	v_exp_f32_e32 v49, v49
	s_waitcnt lgkmcnt(6)
	v_mfma_f32_32x32x16_bf16 v[18:33], v[34:37], v[42:45], v[18:33]
	v_sub_f32_e32 v34, v51, v52
	v_exp_f32_e32 v47, v34
	v_sub_f32_e32 v34, v53, v52
	v_exp_f32_e32 v48, v34
	v_add_f32_e32 v46, v55, v46
	v_ashrrev_i32_e32 v51, 31, v50
	s_waitcnt lgkmcnt(4)
	v_mfma_f32_32x32x16_bf16 v[2:17], v[38:41], v[42:45], v[2:17]
	v_cvt_pk_bf16_f32 v42, v64, v56
	v_cvt_pk_bf16_f32 v43, v57, v58
	v_cvt_pk_bf16_f32 v44, v55, v47
	v_cvt_pk_bf16_f32 v45, v48, v49
	s_lshl_b32 s68, s9, 7
	s_waitcnt lgkmcnt(2)
	v_mfma_f32_32x32x16_bf16 v[18:33], v[148:151], v[42:45], v[18:33]
	v_add_f32_e32 v34, v47, v46
	v_add_f32_e32 v34, v48, v34
	v_add_f32_e32 v34, v49, v34
	ds_bpermute_b32 v35, v171, v34
	s_waitcnt lgkmcnt(0)
	v_add_f32_e32 v36, v34, v35
	v_mfma_f32_32x32x16_bf16 v[2:17], v[152:155], v[42:45], v[2:17]
	v_rcp_f32_e32 v38, v36
	v_lshl_add_u64 v[34:35], s[12:13], 0, v[50:51]
	v_lshlrev_b64 v[40:41], 11, v[34:35]
	v_lshl_add_u64 v[40:41], s[14:15], 0, v[40:41]
	s_nop 0
	v_pk_mul_f32 v[18:19], v[18:19], v[38:39] op_sel_hi:[1,0]
	v_pk_mul_f32 v[20:21], v[20:21], v[38:39] op_sel_hi:[1,0]
	v_cvt_pk_bf16_f32 v18, v18, v19
	s_nop 3
	v_pk_mul_f32 v[2:3], v[2:3], v[38:39] op_sel_hi:[1,0]
	v_pk_mul_f32 v[4:5], v[4:5], v[38:39] op_sel_hi:[1,0]
	v_cvt_pk_bf16_f32 v19, v20, v21
	v_pk_mul_f32 v[20:21], v[22:23], v[38:39] op_sel_hi:[1,0]
	v_pk_mul_f32 v[22:23], v[24:25], v[38:39] op_sel_hi:[1,0]
	v_cvt_pk_bf16_f32 v2, v2, v3
	v_cvt_pk_bf16_f32 v3, v4, v5
	v_pk_mul_f32 v[4:5], v[6:7], v[38:39] op_sel_hi:[1,0]
	v_pk_mul_f32 v[6:7], v[8:9], v[38:39] op_sel_hi:[1,0]
	v_lshl_add_u64 v[40:41], v[40:41], 0, s[68:69]
	v_cvt_pk_bf16_f32 v20, v20, v21
	v_cvt_pk_bf16_f32 v21, v22, v23
	v_cvt_pk_bf16_f32 v4, v4, v5
	v_cvt_pk_bf16_f32 v5, v6, v7
	v_permlane32_swap_b32_e32 v18, v20
	v_permlane32_swap_b32_e32 v19, v21
	v_lshl_add_u64 v[22:23], v[40:41], 0, v[0:1]
	v_permlane32_swap_b32_e32 v2, v4
	v_permlane32_swap_b32_e32 v3, v5
	global_store_dwordx4 v[22:23], v[18:21], off
	global_store_dwordx4 v[22:23], v[2:5], off offset:64
	v_pk_mul_f32 v[24:25], v[32:33], v[38:39] op_sel_hi:[1,0]
	v_pk_mul_f32 v[18:19], v[26:27], v[38:39] op_sel_hi:[1,0]
	v_pk_mul_f32 v[20:21], v[28:29], v[38:39] op_sel_hi:[1,0]
	v_pk_mul_f32 v[2:3], v[10:11], v[38:39] op_sel_hi:[1,0]
	v_pk_mul_f32 v[4:5], v[12:13], v[38:39] op_sel_hi:[1,0]
	v_cvt_pk_bf16_f32 v18, v18, v19
	v_cvt_pk_bf16_f32 v19, v20, v21
	v_pk_mul_f32 v[20:21], v[30:31], v[38:39] op_sel_hi:[1,0]
	v_cvt_pk_bf16_f32 v2, v2, v3
	v_cvt_pk_bf16_f32 v3, v4, v5
	v_pk_mul_f32 v[4:5], v[14:15], v[38:39] op_sel_hi:[1,0]
	v_pk_mul_f32 v[6:7], v[16:17], v[38:39] op_sel_hi:[1,0]
	v_cvt_pk_bf16_f32 v20, v20, v21
	v_cvt_pk_bf16_f32 v21, v24, v25
	v_cvt_pk_bf16_f32 v4, v4, v5
	v_cvt_pk_bf16_f32 v5, v6, v7
	v_permlane32_swap_b32_e32 v18, v20
	v_permlane32_swap_b32_e32 v19, v21
	v_permlane32_swap_b32_e32 v2, v4
	v_permlane32_swap_b32_e32 v3, v5
	global_store_dwordx4 v[22:23], v[18:21], off offset:32
	global_store_dwordx4 v[22:23], v[2:5], off offset:96
	s_and_saveexec_b64 vcc, s[88:89]
	s_cbranch_execz .LBB0_471
	v_log_f32_e32 v2, v36
	s_ashr_i32 s1, s0, 31
	s_lshl_b64 s[0:1], s[0:1], 15
	s_lshl_b32 s68, s9, 2
	v_add_f32_e32 v2, v52, v2
	v_mul_f32_e32 v4, 0x3f317218, v2
	v_lshl_add_u64 v[2:3], v[34:35], 0, s[0:1]
	v_readlane_b32 s0, v253, 63
	v_lshlrev_b64 v[2:3], 6, v[2:3]
	v_readlane_b32 s1, v255, 0
	s_nop 1
	v_lshl_add_u64 v[2:3], s[0:1], 0, v[2:3]
	v_lshl_add_u64 v[2:3], v[2:3], 0, s[68:69]
	global_store_dword v[2:3], v4, off
	s_branch .LBB0_471
